# dt job: 4 row-scale loads issued together, per-row vmcnt(0) drains of write-through stores removed (on top of v23)
# speedup vs baseline: 1.0049x; 1.0016x over previous
;     __device__ __forceinline__ int lane_() const { return hw_lane(); }
; __device__ __forceinline__ void p1b_dt(Frame& F, const Ptrs& P) {
;     ...
;     for (int c = blockIdx.x; c < M / 64; c += F.G) {
;         const int blk = F.G == 256 ? (8 * (c & 7) + ((c >> 3) & 7)) * 4 + (c >> 6) : c;
;         const bf16* ap = XB + (size_t)(blk * 64 + fr) * DM + 8 * fq + 128 * w; const bf16* bp = WIN + (size_t)(NMAIN + fr) * DM + 8 * fq + 128 * w;
;         bf16x8 a[4][4], b[2][4];
; #pragma unroll
;         for (int r = 0; r < 4; ++r)
; #pragma unroll
;             for (int ks = 0; ks < 4; ++ks) a[r][ks] = *(const bf16x8*)(ap + (size_t)(r * 16) * DM + 32 * ks);
; #pragma unroll
;         for (int q = 0; q < 2; ++q)
; #pragma unroll
;             for (int ks = 0; ks < 4; ++ks) b[q][ks] = *(const bf16x8*)(bp + (size_t)(q * 16) * DM + 32 * ks);
; #pragma unroll
;         for (int r = 0; r < 4; ++r)
; #pragma unroll
;             for (int q = 0; q < 2; ++q) { f32x4 acc = (f32x4){0.f, 0.f, 0.f, 0.f};
; #pragma unroll
;                 for (int ks = 0; ks < 4; ++ks) acc = __builtin_amdgcn_mfma_f32_16x16x32_bf16(a[r][ks], b[q][ks], acc, 0, 0, 0);
;                 part[(w * 8 + r * 2 + q) * 64 + lane_] = acc; }
;         __syncthreads();
.LBB0_376:
	s_lshl_b32 s9, s8, 6
	v_or_b32_e32 v0, s9, v56
	v_ashrrev_i32_e32 v1, 31, v0
	v_lshlrev_b64 v[0:1], 11, v[0:1]
	v_lshl_add_u64 v[86:87], v[32:33], 0, v[0:1]
	v_add_co_u32_e32 v98, vcc, 0x8000, v86
	global_load_dwordx4 v[0:3], v[86:87], off
	global_load_dwordx4 v[4:7], v[36:37], off
	global_load_dwordx4 v[8:11], v[36:37], off offset:64
	global_load_dwordx4 v[12:15], v[86:87], off offset:64
	v_addc_co_u32_e32 v99, vcc, 0, v87, vcc
	global_load_dwordx4 v[16:19], v[98:99], off
	v_add_co_u32_e32 v102, vcc, 0x10000, v86
	global_load_dwordx4 v[24:27], v[40:41], off
	global_load_dwordx4 v[28:31], v[42:43], off
	global_load_dwordx4 v[52:55], v[98:99], off offset:64
	v_addc_co_u32_e32 v103, vcc, 0, v87, vcc
	global_load_dwordx4 v[66:69], v[102:103], off
	global_load_dwordx4 v[70:73], v[102:103], off offset:64
	v_add_co_u32_e32 v104, vcc, 0x18000, v86
	s_waitcnt vmcnt(8)
	v_mfma_f32_16x16x32_bf16 v[20:23], v[0:3], v[4:7], 0
	v_addc_co_u32_e32 v105, vcc, 0, v87, vcc
	s_waitcnt vmcnt(4)
	v_mfma_f32_16x16x32_bf16 v[0:3], v[0:3], v[24:27], 0
	v_mfma_f32_16x16x32_bf16 v[62:65], v[16:19], v[4:7], 0
	v_mfma_f32_16x16x32_bf16 v[16:19], v[16:19], v[24:27], 0
	s_waitcnt vmcnt(1)
	v_mfma_f32_16x16x32_bf16 v[74:77], v[66:69], v[4:7], 0
	v_mfma_f32_16x16x32_bf16 v[20:23], v[12:15], v[8:11], v[20:23]
	v_mfma_f32_16x16x32_bf16 v[0:3], v[12:15], v[28:31], v[0:3]
	global_load_dwordx4 v[12:15], v[104:105], off
	global_load_dwordx4 v[78:81], v[104:105], off offset:64
	v_mfma_f32_16x16x32_bf16 v[62:65], v[52:55], v[8:11], v[62:65]
	v_mfma_f32_16x16x32_bf16 v[16:19], v[52:55], v[28:31], v[16:19]
	s_waitcnt vmcnt(2)
	v_mfma_f32_16x16x32_bf16 v[52:55], v[70:73], v[8:11], v[74:77]
	s_nop 2
	global_load_dwordx4 v[74:77], v[86:87], off offset:128
	v_mfma_f32_16x16x32_bf16 v[66:69], v[66:69], v[24:27], 0
	v_mfma_f32_16x16x32_bf16 v[66:69], v[70:73], v[28:31], v[66:69]
	global_load_dwordx4 v[70:73], v[36:37], off offset:128
	global_load_dwordx4 v[82:85], v[36:37], off offset:192
	s_nop 0
	global_load_dwordx4 v[86:89], v[86:87], off offset:192
	s_nop 0
	global_load_dwordx4 v[90:93], v[44:45], off
	global_load_dwordx4 v[94:97], v[46:47], off
	s_waitcnt vmcnt(7)
	v_mfma_f32_16x16x32_bf16 v[4:7], v[12:15], v[4:7], 0
	s_waitcnt vmcnt(4)
	v_mfma_f32_16x16x32_bf16 v[20:23], v[74:77], v[70:73], v[20:23]
	s_waitcnt vmcnt(1)
	v_mfma_f32_16x16x32_bf16 v[0:3], v[74:77], v[90:93], v[0:3]
	v_mfma_f32_16x16x32_bf16 v[4:7], v[78:81], v[8:11], v[4:7]
	global_load_dwordx4 v[8:11], v[98:99], off offset:128
	global_load_dwordx4 v[74:77], v[98:99], off offset:192
	s_nop 0
	global_load_dwordx4 v[98:101], v[102:103], off offset:128
	v_mfma_f32_16x16x32_bf16 v[12:15], v[12:15], v[24:27], 0
	v_mfma_f32_16x16x32_bf16 v[20:23], v[86:89], v[82:85], v[20:23]
	s_waitcnt vmcnt(3)
	v_mfma_f32_16x16x32_bf16 v[0:3], v[86:89], v[94:97], v[0:3]
	v_mfma_f32_16x16x32_bf16 v[12:15], v[78:81], v[28:31], v[12:15]
	s_nop 4
	ds_write_b128 v34, v[20:23]
	s_waitcnt vmcnt(2)
	v_mfma_f32_16x16x32_bf16 v[62:65], v[8:11], v[70:73], v[62:65]
	v_mfma_f32_16x16x32_bf16 v[8:11], v[8:11], v[90:93], v[16:19]
	s_nop 2
	global_load_dwordx4 v[16:19], v[102:103], off offset:192
	s_waitcnt vmcnt(1)
	v_mfma_f32_16x16x32_bf16 v[52:55], v[98:101], v[70:73], v[52:55]
	v_mfma_f32_16x16x32_bf16 v[66:69], v[98:101], v[90:93], v[66:69]
	v_mfma_f32_16x16x32_bf16 v[62:65], v[74:77], v[82:85], v[62:65]
	v_mfma_f32_16x16x32_bf16 v[8:11], v[74:77], v[94:97], v[8:11]
	global_load_dwordx4 v[74:77], v[104:105], off offset:128
	s_waitcnt vmcnt(1)
	v_mfma_f32_16x16x32_bf16 v[52:55], v[16:19], v[82:85], v[52:55]
	v_mfma_f32_16x16x32_bf16 v[16:19], v[16:19], v[94:97], v[66:69]
	s_nop 2
	global_load_dwordx4 v[66:69], v[104:105], off offset:192
	s_waitcnt vmcnt(1)
	v_mfma_f32_16x16x32_bf16 v[4:7], v[74:77], v[70:73], v[4:7]
	ds_write_b128 v34, v[0:3] offset:1024
	ds_write_b128 v34, v[62:65] offset:2048
	ds_write_b128 v34, v[8:11] offset:3072
	v_mfma_f32_16x16x32_bf16 v[0:3], v[74:77], v[90:93], v[12:15]
	s_waitcnt vmcnt(0)
	v_mfma_f32_16x16x32_bf16 v[4:7], v[66:69], v[82:85], v[4:7]
	ds_write_b128 v34, v[52:55] offset:4096
	ds_write_b128 v34, v[16:19] offset:5120
	s_nop 5
	ds_write_b128 v34, v[4:7] offset:6144
	v_add_u32_e32 v52, s9, v57
	v_mfma_f32_16x16x32_bf16 v[0:3], v[66:69], v[94:97], v[0:3]
	v_ashrrev_i32_e32 v53, 31, v52
	v_lshlrev_b64 v[64:65], 7, v[52:53]
	v_or_b32_e32 v54, 1, v52
	v_ashrrev_i32_e32 v55, 31, v54
	s_nop 3
	ds_write_b128 v34, v[0:3] offset:7168
	v_lshl_add_u64 v[0:1], v[52:53], 2, s[6:7]
	s_waitcnt lgkmcnt(0)
	s_barrier
;     __device__ __forceinline__ int lane_() const { return hw_lane(); }
; __device__ __forceinline__ float softplus_f(float v) { return fmaxf(v, 0.f) + log1pf(expf(-fabsf(v))); }
; __device__ __forceinline__ void p1b_dt(Frame& F, const Ptrs& P) {
;     ...
;         f32x4 acc = part[(0 * 8 + rt * 2 + ct) * 64 + lane_];
; #pragma unroll
;         for (int w2 = 1; w2 < 8; ++w2) acc += part[(w2 * 8 + rt * 2 + ct) * 64 + lane_];
;         const int col = ct * 16 + fr; const float bias = col < 16 ? P.dtb_f[col] : P.dtb_b[col - 16];
; #pragma unroll
;         for (int i = 0; i < 4; ++i) { const int row = blk * 64 + rt * 16 + fq * 4 + i;
;             __hip_atomic_store(&DT[(size_t)row * 32 + col], softplus_f(acc[i] * RS[row] + bias), __ATOMIC_RELAXED, __HIP_MEMORY_SCOPE_AGENT); }
	global_load_dword v62, v[48:49], off
	global_load_dword v51, v[0:1], off
	global_load_dword v106, v[0:1], off offset:4
	global_load_dword v107, v[0:1], off offset:8
	global_load_dword v108, v[0:1], off offset:12
	ds_read_b128 v[0:3], v58
	ds_read_b128 v[4:7], v58 offset:8192
	ds_read_b128 v[8:11], v58 offset:16384
	ds_read_b128 v[12:15], v58 offset:24576
	ds_read_b128 v[16:19], v58 offset:32768
	ds_read_b128 v[20:23], v58 offset:40960
	ds_read_b128 v[24:27], v58 offset:49152
	ds_read_b128 v[28:31], v58 offset:57344
	s_waitcnt lgkmcnt(6)
	v_pk_add_f32 v[0:1], v[0:1], v[4:5]
	v_pk_add_f32 v[2:3], v[2:3], v[6:7]
	s_waitcnt lgkmcnt(5)
	v_pk_add_f32 v[0:1], v[0:1], v[8:9]
	v_pk_add_f32 v[2:3], v[2:3], v[10:11]
	s_waitcnt lgkmcnt(4)
	v_pk_add_f32 v[0:1], v[0:1], v[12:13]
	v_pk_add_f32 v[2:3], v[2:3], v[14:15]
	s_waitcnt lgkmcnt(3)
	v_pk_add_f32 v[0:1], v[0:1], v[16:17]
	v_pk_add_f32 v[2:3], v[2:3], v[18:19]
	s_waitcnt lgkmcnt(2)
	v_pk_add_f32 v[0:1], v[0:1], v[20:21]
	v_pk_add_f32 v[2:3], v[2:3], v[22:23]
	s_waitcnt lgkmcnt(1)
	v_pk_add_f32 v[0:1], v[0:1], v[24:25]
	v_pk_add_f32 v[2:3], v[2:3], v[26:27]
	s_waitcnt lgkmcnt(0)
	v_pk_add_f32 v[4:5], v[0:1], v[28:29]
	v_pk_add_f32 v[2:3], v[2:3], v[30:31]
	s_waitcnt vmcnt(0)
	v_fma_f32 v4, v4, v51, v62
	v_mul_f32_e64 v0, |v4|, s12
	v_fma_f32 v1, |v4|, s12, -v0
	v_rndne_f32_e32 v8, v0
	v_fma_f32 v1, |v4|, s17, v1
	v_sub_f32_e32 v0, v0, v8
	v_add_f32_e32 v0, v0, v1
	v_cvt_i32_f32_e32 v12, v8
	v_exp_f32_e32 v13, v0
	v_cmp_ngt_f32_e64 vcc, |v4|, s20
	v_max_f32_e32 v53, 0, v4
	v_lshl_add_u64 v[0:1], v[38:39], 0, v[64:65]
	v_ldexp_f32 v12, v13, v12
	v_cndmask_b32_e32 v12, 0, v12, vcc
	v_cmp_nlt_f32_e64 vcc, |v4|, s21
	v_lshl_add_u64 v[8:9], v[54:55], 2, s[6:7]
	s_nop 0
	v_cndmask_b32_e32 v4, v59, v12, vcc
	v_add_f32_e32 v16, 1.0, v4
	v_add_f32_e32 v17, -1.0, v16
	v_frexp_mant_f32_e32 v20, v16
	v_cvt_f64_f32_e32 v[12:13], v16
	v_sub_f32_e32 v21, v17, v16
	v_frexp_exp_i32_f64_e32 v12, v[12:13]
	v_cmp_gt_f32_e32 vcc, s23, v20
	v_sub_f32_e32 v17, v4, v17
	v_add_f32_e32 v13, 1.0, v21
	v_subbrev_co_u32_e32 v12, vcc, 0, v12, vcc
	v_add_f32_e32 v13, v17, v13
	v_sub_u32_e32 v17, 0, v12
	v_ldexp_f32 v16, v16, v17
	v_add_f32_e32 v20, -1.0, v16
	v_add_f32_e32 v21, 1.0, v16
	v_ldexp_f32 v13, v13, v17
	v_add_f32_e32 v17, 1.0, v20
	v_add_f32_e32 v24, -1.0, v21
	v_sub_f32_e32 v17, v16, v17
	v_sub_f32_e32 v16, v16, v24
	v_add_f32_e32 v24, v13, v17
	v_add_f32_e32 v13, v13, v16
	v_add_f32_e32 v28, v21, v13
	v_rcp_f32_e32 v29, v28
	v_add_f32_e32 v17, v20, v24
	v_sub_f32_e32 v20, v20, v17
	v_sub_f32_e32 v16, v21, v28
	v_mul_f32_e32 v63, v17, v29
	v_add_f32_e32 v51, v24, v20
	v_mul_f32_e32 v20, v28, v63
	v_add_f32_e32 v13, v13, v16
	v_fma_f32 v24, v63, v28, -v20
	v_fmac_f32_e32 v24, v63, v13
	v_add_f32_e32 v16, v20, v24
	v_sub_f32_e32 v21, v17, v16
	v_mov_b32_e32 v25, v16
	v_pk_add_f32 v[16:17], v[16:17], v[20:21] neg_lo:[0,1] neg_hi:[0,1]
	v_cvt_f32_i32_e32 v12, v12
	v_pk_add_f32 v[16:17], v[16:17], v[24:25] neg_lo:[0,1] neg_hi:[0,1]
	v_cmp_neq_f32_e32 vcc, s22, v4
	v_add_f32_e32 v17, v51, v17
	v_add_f32_e32 v16, v16, v17
	v_add_f32_e32 v17, v21, v16
	v_mul_f32_e32 v25, v29, v17
	v_mul_f32_e32 v20, v28, v25
	v_sub_f32_e32 v21, v21, v17
	v_add_f32_e32 v64, v63, v25
	v_fma_f32 v24, v25, v28, -v20
	v_add_f32_e32 v51, v16, v21
	v_sub_f32_e32 v16, v64, v63
	v_fmac_f32_e32 v24, v25, v13
	v_sub_f32_e32 v13, v25, v16
	v_add_f32_e32 v16, v20, v24
	v_sub_f32_e32 v21, v17, v16
	v_mov_b32_e32 v25, v16
	v_pk_add_f32 v[16:17], v[16:17], v[20:21] neg_lo:[0,1] neg_hi:[0,1]
	s_nop 0
	v_pk_add_f32 v[16:17], v[16:17], v[24:25] neg_lo:[0,1] neg_hi:[0,1]
	s_nop 0
	v_add_f32_e32 v17, v51, v17
	v_add_f32_e32 v16, v16, v17
	v_add_f32_e32 v16, v21, v16
	v_mul_f32_e32 v16, v29, v16
	v_add_f32_e32 v13, v13, v16
	v_add_f32_e32 v16, v64, v13
	v_mul_f32_e32 v20, v16, v16
	v_sub_f32_e32 v21, v16, v64
	v_fmamk_f32 v24, v20, 0x3e9b6dac, v60
	v_sub_f32_e32 v21, v13, v21
	v_mul_f32_e32 v13, v16, v20
	v_fmaak_f32 v51, v20, v24, 0x3f2aaada
	v_ldexp_f32 v25, v21, 1
	v_pk_mul_f32 v[20:21], v[12:13], v[50:51]
	v_ldexp_f32 v17, v16, 1
	v_fma_f32 v16, v12, s28, -v20
	v_fmac_f32_e32 v16, 0xb102e308, v12
	v_pk_add_f32 v[12:13], v[20:21], v[16:17]
	v_mov_b32_e32 v24, v20
	v_sub_f32_e32 v51, v13, v17
	v_pk_add_f32 v[28:29], v[12:13], v[20:21] neg_lo:[0,1] neg_hi:[0,1]
	v_sub_f32_e32 v20, v21, v51
	v_add_f32_e32 v25, v25, v20
	v_pk_add_f32 v[20:21], v[12:13], v[24:25]
	v_mov_b32_e32 v17, v12
	v_mov_b32_e32 v29, v21
	v_pk_add_f32 v[66:67], v[16:17], v[28:29] neg_lo:[0,1] neg_hi:[0,1]
	v_pk_add_f32 v[16:17], v[16:17], v[28:29]
	v_mov_b32_e32 v65, v12
	v_pk_add_f32 v[28:29], v[16:17], v[12:13] op_sel:[1,0] op_sel_hi:[0,1] neg_lo:[0,1] neg_hi:[0,1]
	v_mov_b32_e32 v64, v25
	v_mov_b32_e32 v24, v21
	v_mov_b32_e32 v25, v17
	v_pk_mov_b32 v[12:13], v[12:13], v[28:29] op_sel:[1,0]
	v_pk_add_f32 v[20:21], v[20:21], v[28:29] op_sel_hi:[1,0] neg_lo:[0,1] neg_hi:[0,1]
	v_pk_add_f32 v[12:13], v[24:25], v[12:13] neg_lo:[0,1] neg_hi:[0,1]
	v_mov_b32_e32 v20, v66
	v_pk_add_f32 v[12:13], v[64:65], v[12:13] neg_lo:[0,1] neg_hi:[0,1]
	v_mov_b32_e32 v67, v17
	v_pk_add_f32 v[20:21], v[20:21], v[12:13]
	s_nop 0
	v_pk_add_f32 v[24:25], v[20:21], v[20:21] op_sel:[0,1] op_sel_hi:[1,0]
	s_nop 0
	v_pk_add_f32 v[16:17], v[16:17], v[24:25] op_sel:[1,0] op_sel_hi:[0,1]
	v_mov_b32_e32 v21, v16
	v_mov_b32_e32 v13, v24
	v_pk_add_f32 v[24:25], v[20:21], v[66:67] neg_lo:[0,1] neg_hi:[0,1]
	s_nop 0
	v_sub_f32_e32 v17, v20, v24
	v_pk_add_f32 v[12:13], v[12:13], v[24:25] neg_lo:[0,1] neg_hi:[0,1]
	v_sub_f32_e32 v17, v66, v17
	v_add_f32_e32 v12, v12, v17
	v_add_f32_e32 v12, v12, v13
	v_add_f32_e32 v12, v16, v12
; __device__ __forceinline__ float softplus_f(float v) { return fmaxf(v, 0.f) + log1pf(expf(-fabsf(v))); }
; __device__ __forceinline__ void p1b_dt(Frame& F, const Ptrs& P) {
;     ...
;         for (int i = 0; i < 4; ++i) { const int row = blk * 64 + rt * 16 + fq * 4 + i;
;             __hip_atomic_store(&DT[(size_t)row * 32 + col], softplus_f(acc[i] * RS[row] + bias), __ATOMIC_RELAXED, __HIP_MEMORY_SCOPE_AGENT); }
	v_cndmask_b32_e32 v12, v59, v12, vcc
	v_cmp_lt_f32_e64 vcc, |v4|, s29
	s_nop 1
	v_cndmask_b32_e32 v4, v12, v4, vcc
	v_add_f32_e32 v4, v53, v4
	global_store_dword v[0:1], v4, off sc1
	v_mov_b32_e32 v4, v106
	v_lshlrev_b64 v[8:9], 7, v[54:55]
	v_or_b32_e32 v0, 2, v52
	v_ashrrev_i32_e32 v1, 31, v0
	v_lshl_add_u64 v[8:9], v[38:39], 0, v[8:9]
	s_nop 0
	v_fma_f32 v12, v5, v4, v62
	v_mul_f32_e64 v4, |v12|, s12
	v_fma_f32 v5, |v12|, s12, -v4
	v_rndne_f32_e32 v13, v4
	v_fma_f32 v5, |v12|, s17, v5
	v_sub_f32_e32 v4, v4, v13
	v_add_f32_e32 v4, v4, v5
	v_cvt_i32_f32_e32 v13, v13
	v_exp_f32_e32 v16, v4
	v_cmp_ngt_f32_e64 vcc, |v12|, s20
	v_max_f32_e32 v53, 0, v12
	v_lshl_add_u64 v[4:5], v[0:1], 2, s[6:7]
	v_ldexp_f32 v13, v16, v13
	v_cndmask_b32_e32 v13, 0, v13, vcc
	v_cmp_nlt_f32_e64 vcc, |v12|, s21
	v_lshlrev_b64 v[0:1], 7, v[0:1]
	v_lshl_add_u64 v[0:1], v[38:39], 0, v[0:1]
	v_cndmask_b32_e32 v63, v59, v13, vcc
	v_add_f32_e32 v16, 1.0, v63
	v_add_f32_e32 v17, -1.0, v16
	v_frexp_mant_f32_e32 v20, v16
	v_cvt_f64_f32_e32 v[12:13], v16
	v_sub_f32_e32 v21, v17, v16
	v_frexp_exp_i32_f64_e32 v12, v[12:13]
	v_cmp_gt_f32_e32 vcc, s23, v20
	v_sub_f32_e32 v17, v63, v17
	v_add_f32_e32 v13, 1.0, v21
	v_subbrev_co_u32_e32 v12, vcc, 0, v12, vcc
	v_add_f32_e32 v13, v17, v13
	v_sub_u32_e32 v17, 0, v12
	v_ldexp_f32 v16, v16, v17
	v_add_f32_e32 v20, -1.0, v16
	v_add_f32_e32 v21, 1.0, v16
	v_ldexp_f32 v13, v13, v17
	v_add_f32_e32 v17, 1.0, v20
	v_add_f32_e32 v24, -1.0, v21
	v_sub_f32_e32 v17, v16, v17
	v_sub_f32_e32 v16, v16, v24
	v_add_f32_e32 v24, v13, v17
	v_add_f32_e32 v13, v13, v16
	v_add_f32_e32 v28, v21, v13
	v_rcp_f32_e32 v29, v28
	v_add_f32_e32 v17, v20, v24
	v_sub_f32_e32 v20, v20, v17
	v_sub_f32_e32 v16, v21, v28
	v_mul_f32_e32 v54, v17, v29
	v_add_f32_e32 v51, v24, v20
	v_mul_f32_e32 v20, v28, v54
	v_add_f32_e32 v13, v13, v16
	v_fma_f32 v24, v54, v28, -v20
	v_fmac_f32_e32 v24, v54, v13
	v_add_f32_e32 v16, v20, v24
	v_sub_f32_e32 v21, v17, v16
	v_mov_b32_e32 v25, v16
	v_pk_add_f32 v[16:17], v[16:17], v[20:21] neg_lo:[0,1] neg_hi:[0,1]
	v_cvt_f32_i32_e32 v12, v12
	v_pk_add_f32 v[16:17], v[16:17], v[24:25] neg_lo:[0,1] neg_hi:[0,1]
	v_cmp_neq_f32_e32 vcc, s22, v63
	v_add_f32_e32 v17, v51, v17
	v_add_f32_e32 v16, v16, v17
	v_add_f32_e32 v17, v21, v16
	v_mul_f32_e32 v25, v29, v17
	v_mul_f32_e32 v20, v28, v25
	v_sub_f32_e32 v21, v21, v17
	v_add_f32_e32 v55, v54, v25
	v_fma_f32 v24, v25, v28, -v20
	v_add_f32_e32 v51, v16, v21
	v_sub_f32_e32 v16, v55, v54
	v_fmac_f32_e32 v24, v25, v13
	v_sub_f32_e32 v13, v25, v16
	v_add_f32_e32 v16, v20, v24
	v_sub_f32_e32 v21, v17, v16
	v_mov_b32_e32 v25, v16
	v_pk_add_f32 v[16:17], v[16:17], v[20:21] neg_lo:[0,1] neg_hi:[0,1]
	s_nop 0
	v_pk_add_f32 v[16:17], v[16:17], v[24:25] neg_lo:[0,1] neg_hi:[0,1]
	s_nop 0
	v_add_f32_e32 v17, v51, v17
	v_add_f32_e32 v16, v16, v17
	v_add_f32_e32 v16, v21, v16
	v_mul_f32_e32 v16, v29, v16
	v_add_f32_e32 v13, v13, v16
	v_add_f32_e32 v16, v55, v13
	v_mul_f32_e32 v20, v16, v16
	v_sub_f32_e32 v21, v16, v55
	v_fmamk_f32 v24, v20, 0x3e9b6dac, v60
	v_sub_f32_e32 v21, v13, v21
	v_mul_f32_e32 v13, v16, v20
	v_fmaak_f32 v51, v20, v24, 0x3f2aaada
	v_ldexp_f32 v25, v21, 1
	v_pk_mul_f32 v[20:21], v[12:13], v[50:51]
	v_ldexp_f32 v17, v16, 1
	v_fma_f32 v16, v12, s28, -v20
	v_fmac_f32_e32 v16, 0xb102e308, v12
	v_pk_add_f32 v[12:13], v[20:21], v[16:17]
	v_mov_b32_e32 v24, v20
	v_sub_f32_e32 v51, v13, v17
	v_pk_add_f32 v[28:29], v[12:13], v[20:21] neg_lo:[0,1] neg_hi:[0,1]
	v_sub_f32_e32 v20, v21, v51
	v_add_f32_e32 v25, v25, v20
	v_pk_add_f32 v[20:21], v[12:13], v[24:25]
	v_mov_b32_e32 v17, v12
	v_mov_b32_e32 v29, v21
	v_pk_add_f32 v[64:65], v[16:17], v[28:29] neg_lo:[0,1] neg_hi:[0,1]
	v_pk_add_f32 v[16:17], v[16:17], v[28:29]
	v_mov_b32_e32 v55, v12
	v_pk_add_f32 v[28:29], v[16:17], v[12:13] op_sel:[1,0] op_sel_hi:[0,1] neg_lo:[0,1] neg_hi:[0,1]
	v_mov_b32_e32 v54, v25
	v_mov_b32_e32 v24, v21
	v_mov_b32_e32 v25, v17
	v_pk_mov_b32 v[12:13], v[12:13], v[28:29] op_sel:[1,0]
	v_pk_add_f32 v[20:21], v[20:21], v[28:29] op_sel_hi:[1,0] neg_lo:[0,1] neg_hi:[0,1]
	v_pk_add_f32 v[12:13], v[24:25], v[12:13] neg_lo:[0,1] neg_hi:[0,1]
	v_mov_b32_e32 v20, v64
	v_pk_add_f32 v[12:13], v[54:55], v[12:13] neg_lo:[0,1] neg_hi:[0,1]
	v_mov_b32_e32 v65, v17
	v_pk_add_f32 v[20:21], v[20:21], v[12:13]
	s_nop 0
	v_pk_add_f32 v[24:25], v[20:21], v[20:21] op_sel:[0,1] op_sel_hi:[1,0]
	s_nop 0
	v_pk_add_f32 v[16:17], v[16:17], v[24:25] op_sel:[1,0] op_sel_hi:[0,1]
	v_mov_b32_e32 v21, v16
	v_mov_b32_e32 v13, v24
	v_pk_add_f32 v[24:25], v[20:21], v[64:65] neg_lo:[0,1] neg_hi:[0,1]
	s_nop 0
	v_sub_f32_e32 v17, v20, v24
	v_pk_add_f32 v[12:13], v[12:13], v[24:25] neg_lo:[0,1] neg_hi:[0,1]
	v_sub_f32_e32 v17, v64, v17
	v_add_f32_e32 v12, v12, v17
	v_add_f32_e32 v12, v12, v13
	v_add_f32_e32 v12, v16, v12
	v_cndmask_b32_e32 v12, v59, v12, vcc
	v_cmp_lt_f32_e64 vcc, |v63|, s29
	s_nop 1
	v_cndmask_b32_e32 v12, v12, v63, vcc
	v_add_f32_e32 v12, v53, v12
	global_store_dword v[8:9], v12, off sc1
	v_mov_b32_e32 v8, v107
	v_or_b32_e32 v4, 3, v52
	v_ashrrev_i32_e32 v5, 31, v4
	s_nop 0
	v_fma_f32 v2, v2, v8, v62
	v_mul_f32_e64 v6, |v2|, s12
	v_fma_f32 v7, |v2|, s12, -v6
	v_rndne_f32_e32 v8, v6
	v_fma_f32 v7, |v2|, s17, v7
	v_sub_f32_e32 v6, v6, v8
	v_add_f32_e32 v6, v6, v7
	v_cvt_i32_f32_e32 v8, v8
	v_exp_f32_e32 v9, v6
	v_cmp_ngt_f32_e64 vcc, |v2|, s20
	v_max_f32_e32 v22, 0, v2
	v_lshl_add_u64 v[6:7], v[4:5], 2, s[6:7]
	v_ldexp_f32 v8, v9, v8
	v_cndmask_b32_e32 v8, 0, v8, vcc
	v_cmp_nlt_f32_e64 vcc, |v2|, s21
	s_nop 1
	v_cndmask_b32_e32 v2, v59, v8, vcc
	v_add_f32_e32 v10, 1.0, v2
	v_add_f32_e32 v11, -1.0, v10
	v_frexp_mant_f32_e32 v12, v10
; __device__ __forceinline__ float softplus_f(float v) { return fmaxf(v, 0.f) + log1pf(expf(-fabsf(v))); }
; __device__ __forceinline__ void p1b_dt(Frame& F, const Ptrs& P) {
;     ...
;         for (int i = 0; i < 4; ++i) { const int row = blk * 64 + rt * 16 + fq * 4 + i;
;             __hip_atomic_store(&DT[(size_t)row * 32 + col], softplus_f(acc[i] * RS[row] + bias), __ATOMIC_RELAXED, __HIP_MEMORY_SCOPE_AGENT); }
	v_cvt_f64_f32_e32 v[8:9], v10
	v_sub_f32_e32 v13, v11, v10
	v_frexp_exp_i32_f64_e32 v8, v[8:9]
	v_cmp_gt_f32_e32 vcc, s23, v12
	v_sub_f32_e32 v11, v2, v11
	v_add_f32_e32 v9, 1.0, v13
	v_subbrev_co_u32_e32 v8, vcc, 0, v8, vcc
	v_add_f32_e32 v9, v11, v9
	v_sub_u32_e32 v11, 0, v8
	v_ldexp_f32 v10, v10, v11
	v_add_f32_e32 v12, -1.0, v10
	v_add_f32_e32 v13, 1.0, v10
	v_ldexp_f32 v9, v9, v11
	v_add_f32_e32 v11, 1.0, v12
	v_add_f32_e32 v14, -1.0, v13
	v_sub_f32_e32 v11, v10, v11
	v_sub_f32_e32 v10, v10, v14
	v_add_f32_e32 v14, v9, v11
	v_add_f32_e32 v9, v9, v10
	v_add_f32_e32 v16, v13, v9
	v_rcp_f32_e32 v17, v16
	v_add_f32_e32 v11, v12, v14
	v_sub_f32_e32 v12, v12, v11
	v_sub_f32_e32 v10, v13, v16
	v_mul_f32_e32 v19, v11, v17
	v_add_f32_e32 v18, v14, v12
	v_mul_f32_e32 v12, v16, v19
	v_add_f32_e32 v9, v9, v10
	v_fma_f32 v14, v19, v16, -v12
	v_fmac_f32_e32 v14, v19, v9
	v_add_f32_e32 v10, v12, v14
	v_sub_f32_e32 v13, v11, v10
	v_mov_b32_e32 v15, v10
	v_pk_add_f32 v[10:11], v[10:11], v[12:13] neg_lo:[0,1] neg_hi:[0,1]
	v_cvt_f32_i32_e32 v8, v8
	v_pk_add_f32 v[10:11], v[10:11], v[14:15] neg_lo:[0,1] neg_hi:[0,1]
	v_cmp_neq_f32_e32 vcc, s22, v2
	v_add_f32_e32 v11, v18, v11
	v_add_f32_e32 v10, v10, v11
	v_add_f32_e32 v11, v13, v10
	v_mul_f32_e32 v15, v17, v11
	v_mul_f32_e32 v12, v16, v15
	v_sub_f32_e32 v13, v13, v11
	v_add_f32_e32 v20, v19, v15
	v_fma_f32 v14, v15, v16, -v12
	v_add_f32_e32 v18, v10, v13
	v_sub_f32_e32 v10, v20, v19
	v_fmac_f32_e32 v14, v15, v9
	v_sub_f32_e32 v9, v15, v10
	v_add_f32_e32 v10, v12, v14
	v_sub_f32_e32 v13, v11, v10
	v_mov_b32_e32 v15, v10
	v_pk_add_f32 v[10:11], v[10:11], v[12:13] neg_lo:[0,1] neg_hi:[0,1]
	s_nop 0
	v_pk_add_f32 v[10:11], v[10:11], v[14:15] neg_lo:[0,1] neg_hi:[0,1]
	s_nop 0
	v_add_f32_e32 v11, v18, v11
	v_add_f32_e32 v10, v10, v11
	v_add_f32_e32 v10, v13, v10
	v_mul_f32_e32 v10, v17, v10
	v_add_f32_e32 v9, v9, v10
	v_add_f32_e32 v10, v20, v9
	v_mul_f32_e32 v12, v10, v10
	v_sub_f32_e32 v13, v10, v20
	v_fmamk_f32 v14, v12, 0x3e9b6dac, v60
	v_sub_f32_e32 v13, v9, v13
	v_mul_f32_e32 v9, v10, v12
	v_fmaak_f32 v51, v12, v14, 0x3f2aaada
	v_ldexp_f32 v15, v13, 1
	v_pk_mul_f32 v[12:13], v[8:9], v[50:51]
	v_ldexp_f32 v11, v10, 1
	v_fma_f32 v10, v8, s28, -v12
	v_fmac_f32_e32 v10, 0xb102e308, v8
	v_pk_add_f32 v[8:9], v[12:13], v[10:11]
	v_mov_b32_e32 v14, v12
	v_sub_f32_e32 v18, v9, v11
	v_pk_add_f32 v[16:17], v[8:9], v[12:13] neg_lo:[0,1] neg_hi:[0,1]
	v_sub_f32_e32 v12, v13, v18
	v_add_f32_e32 v15, v15, v12
	v_pk_add_f32 v[12:13], v[8:9], v[14:15]
	v_mov_b32_e32 v11, v8
	v_mov_b32_e32 v17, v13
	v_pk_add_f32 v[20:21], v[10:11], v[16:17] neg_lo:[0,1] neg_hi:[0,1]
	v_pk_add_f32 v[10:11], v[10:11], v[16:17]
	v_mov_b32_e32 v19, v8
	v_pk_add_f32 v[16:17], v[10:11], v[8:9] op_sel:[1,0] op_sel_hi:[0,1] neg_lo:[0,1] neg_hi:[0,1]
	v_mov_b32_e32 v18, v15
	v_mov_b32_e32 v14, v13
	v_mov_b32_e32 v15, v11
	v_pk_mov_b32 v[8:9], v[8:9], v[16:17] op_sel:[1,0]
	v_pk_add_f32 v[12:13], v[12:13], v[16:17] op_sel_hi:[1,0] neg_lo:[0,1] neg_hi:[0,1]
	v_pk_add_f32 v[8:9], v[14:15], v[8:9] neg_lo:[0,1] neg_hi:[0,1]
	v_mov_b32_e32 v12, v20
	v_pk_add_f32 v[8:9], v[18:19], v[8:9] neg_lo:[0,1] neg_hi:[0,1]
	v_mov_b32_e32 v21, v11
	v_pk_add_f32 v[12:13], v[12:13], v[8:9]
	s_nop 0
	v_pk_add_f32 v[14:15], v[12:13], v[12:13] op_sel:[0,1] op_sel_hi:[1,0]
	s_nop 0
	v_pk_add_f32 v[10:11], v[10:11], v[14:15] op_sel:[1,0] op_sel_hi:[0,1]
	v_mov_b32_e32 v13, v10
	v_mov_b32_e32 v9, v14
	v_pk_add_f32 v[14:15], v[12:13], v[20:21] neg_lo:[0,1] neg_hi:[0,1]
	s_nop 0
	v_sub_f32_e32 v11, v12, v14
	v_pk_add_f32 v[8:9], v[8:9], v[14:15] neg_lo:[0,1] neg_hi:[0,1]
	v_sub_f32_e32 v11, v20, v11
	v_add_f32_e32 v8, v8, v11
	v_add_f32_e32 v8, v8, v9
	v_add_f32_e32 v8, v10, v8
	v_cndmask_b32_e32 v8, v59, v8, vcc
	v_cmp_lt_f32_e64 vcc, |v2|, s29
	s_nop 1
	v_cndmask_b32_e32 v2, v8, v2, vcc
	v_add_f32_e32 v2, v22, v2
	global_store_dword v[0:1], v2, off sc1
	v_mov_b32_e32 v0, v108
	s_nop 0
	v_fmac_f32_e32 v62, v3, v0
	v_mul_f32_e64 v0, |v62|, s12
	v_fma_f32 v1, |v62|, s12, -v0
	v_rndne_f32_e32 v2, v0
	v_fma_f32 v1, |v62|, s17, v1
	v_sub_f32_e32 v0, v0, v2
	v_add_f32_e32 v0, v0, v1
	v_cvt_i32_f32_e32 v2, v2
	v_exp_f32_e32 v3, v0
	v_cmp_ngt_f32_e64 vcc, |v62|, s20
	v_lshlrev_b64 v[0:1], 7, v[4:5]
; __device__ __forceinline__ float softplus_f(float v) { return fmaxf(v, 0.f) + log1pf(expf(-fabsf(v))); }
;     __device__ __forceinline__ int lane_() const { return hw_lane(); }
; __device__ __forceinline__ void p1b_dt(Frame& F, const Ptrs& P) {
;     ...
;         for (int i = 0; i < 4; ++i) { const int row = blk * 64 + rt * 16 + fq * 4 + i;
;             __hip_atomic_store(&DT[(size_t)row * 32 + col], softplus_f(acc[i] * RS[row] + bias), __ATOMIC_RELAXED, __HIP_MEMORY_SCOPE_AGENT); }
;         asm volatile("s_waitcnt vmcnt(0)" ::: "memory");
;         __syncthreads();
;         if (w == 0 && lane_ == 0) __hip_atomic_store((unsigned*)(P.ws + WS_CTL) + CW_DTF + blk, 1u, __ATOMIC_RELAXED, __HIP_MEMORY_SCOPE_AGENT);
;     }
	v_max_f32_e32 v16, 0, v62
	v_ldexp_f32 v2, v3, v2
	v_cndmask_b32_e32 v2, 0, v2, vcc
	v_cmp_nlt_f32_e64 vcc, |v62|, s21
	v_lshl_add_u64 v[0:1], v[38:39], 0, v[0:1]
	s_nop 0
	v_cndmask_b32_e32 v17, v59, v2, vcc
	v_add_f32_e32 v4, 1.0, v17
	v_add_f32_e32 v5, -1.0, v4
	v_frexp_mant_f32_e32 v6, v4
	v_cvt_f64_f32_e32 v[2:3], v4
	v_sub_f32_e32 v7, v5, v4
	v_frexp_exp_i32_f64_e32 v2, v[2:3]
	v_cmp_gt_f32_e32 vcc, s23, v6
	v_sub_f32_e32 v5, v17, v5
	v_add_f32_e32 v3, 1.0, v7
	v_subbrev_co_u32_e32 v2, vcc, 0, v2, vcc
	v_add_f32_e32 v3, v5, v3
	v_sub_u32_e32 v5, 0, v2
	v_ldexp_f32 v4, v4, v5
	v_add_f32_e32 v6, -1.0, v4
	v_add_f32_e32 v7, 1.0, v4
	v_ldexp_f32 v3, v3, v5
	v_add_f32_e32 v5, 1.0, v6
	v_add_f32_e32 v8, -1.0, v7
	v_sub_f32_e32 v5, v4, v5
	v_sub_f32_e32 v4, v4, v8
	v_add_f32_e32 v8, v3, v5
	v_add_f32_e32 v3, v3, v4
	v_add_f32_e32 v10, v7, v3
	v_rcp_f32_e32 v11, v10
	v_add_f32_e32 v5, v6, v8
	v_sub_f32_e32 v6, v6, v5
	v_sub_f32_e32 v4, v7, v10
	v_mul_f32_e32 v13, v5, v11
	v_add_f32_e32 v12, v8, v6
	v_mul_f32_e32 v6, v10, v13
	v_add_f32_e32 v3, v3, v4
	v_fma_f32 v8, v13, v10, -v6
	v_fmac_f32_e32 v8, v13, v3
	v_add_f32_e32 v4, v6, v8
	v_sub_f32_e32 v7, v5, v4
	v_mov_b32_e32 v9, v4
	v_pk_add_f32 v[4:5], v[4:5], v[6:7] neg_lo:[0,1] neg_hi:[0,1]
	v_cvt_f32_i32_e32 v2, v2
	v_pk_add_f32 v[4:5], v[4:5], v[8:9] neg_lo:[0,1] neg_hi:[0,1]
	v_cmp_neq_f32_e32 vcc, s22, v17
	v_add_f32_e32 v5, v12, v5
	v_add_f32_e32 v4, v4, v5
	v_add_f32_e32 v5, v7, v4
	v_mul_f32_e32 v9, v11, v5
	v_mul_f32_e32 v6, v10, v9
	v_sub_f32_e32 v7, v7, v5
	v_add_f32_e32 v14, v13, v9
	v_fma_f32 v8, v9, v10, -v6
	v_add_f32_e32 v12, v4, v7
	v_sub_f32_e32 v4, v14, v13
	v_fmac_f32_e32 v8, v9, v3
	v_sub_f32_e32 v3, v9, v4
	v_add_f32_e32 v4, v6, v8
	v_sub_f32_e32 v7, v5, v4
	v_mov_b32_e32 v9, v4
	v_pk_add_f32 v[4:5], v[4:5], v[6:7] neg_lo:[0,1] neg_hi:[0,1]
	s_nop 0
	v_pk_add_f32 v[4:5], v[4:5], v[8:9] neg_lo:[0,1] neg_hi:[0,1]
	s_nop 0
	v_add_f32_e32 v5, v12, v5
	v_add_f32_e32 v4, v4, v5
	v_add_f32_e32 v4, v7, v4
	v_mul_f32_e32 v4, v11, v4
	v_add_f32_e32 v3, v3, v4
	v_add_f32_e32 v4, v14, v3
	v_mul_f32_e32 v6, v4, v4
	v_sub_f32_e32 v7, v4, v14
	v_fmamk_f32 v8, v6, 0x3e9b6dac, v60
	v_sub_f32_e32 v7, v3, v7
	v_mul_f32_e32 v3, v4, v6
	v_fmaak_f32 v51, v6, v8, 0x3f2aaada
	v_ldexp_f32 v9, v7, 1
	v_pk_mul_f32 v[6:7], v[2:3], v[50:51]
	v_ldexp_f32 v5, v4, 1
	v_fma_f32 v4, v2, s28, -v6
	v_fmac_f32_e32 v4, 0xb102e308, v2
	v_pk_add_f32 v[2:3], v[6:7], v[4:5]
	v_mov_b32_e32 v8, v6
	v_sub_f32_e32 v12, v3, v5
	v_pk_add_f32 v[10:11], v[2:3], v[6:7] neg_lo:[0,1] neg_hi:[0,1]
	v_sub_f32_e32 v6, v7, v12
	v_add_f32_e32 v9, v9, v6
	v_pk_add_f32 v[6:7], v[2:3], v[8:9]
	v_mov_b32_e32 v5, v2
	v_mov_b32_e32 v11, v7
	v_pk_add_f32 v[14:15], v[4:5], v[10:11] neg_lo:[0,1] neg_hi:[0,1]
	v_pk_add_f32 v[4:5], v[4:5], v[10:11]
	v_mov_b32_e32 v13, v2
	v_pk_add_f32 v[10:11], v[4:5], v[2:3] op_sel:[1,0] op_sel_hi:[0,1] neg_lo:[0,1] neg_hi:[0,1]
	v_mov_b32_e32 v12, v9
	v_mov_b32_e32 v8, v7
	v_mov_b32_e32 v9, v5
	v_pk_mov_b32 v[2:3], v[2:3], v[10:11] op_sel:[1,0]
	v_pk_add_f32 v[6:7], v[6:7], v[10:11] op_sel_hi:[1,0] neg_lo:[0,1] neg_hi:[0,1]
	v_pk_add_f32 v[2:3], v[8:9], v[2:3] neg_lo:[0,1] neg_hi:[0,1]
	v_mov_b32_e32 v6, v14
	v_pk_add_f32 v[2:3], v[12:13], v[2:3] neg_lo:[0,1] neg_hi:[0,1]
	v_mov_b32_e32 v15, v5
	v_pk_add_f32 v[6:7], v[6:7], v[2:3]
	s_nop 0
	v_pk_add_f32 v[8:9], v[6:7], v[6:7] op_sel:[0,1] op_sel_hi:[1,0]
	s_nop 0
	v_pk_add_f32 v[4:5], v[4:5], v[8:9] op_sel:[1,0] op_sel_hi:[0,1]
	v_mov_b32_e32 v7, v4
	v_mov_b32_e32 v3, v8
	v_pk_add_f32 v[8:9], v[6:7], v[14:15] neg_lo:[0,1] neg_hi:[0,1]
	s_nop 0
	v_sub_f32_e32 v5, v6, v8
	v_pk_add_f32 v[2:3], v[2:3], v[8:9] neg_lo:[0,1] neg_hi:[0,1]
	v_sub_f32_e32 v5, v14, v5
	v_add_f32_e32 v2, v2, v5
	v_add_f32_e32 v2, v2, v3
	v_add_f32_e32 v2, v4, v2
	v_cndmask_b32_e32 v2, v59, v2, vcc
	v_cmp_lt_f32_e64 vcc, |v17|, s29
	s_nop 1
	v_cndmask_b32_e32 v2, v2, v17, vcc
	v_add_f32_e32 v2, v16, v2
	global_store_dword v[0:1], v2, off sc1
	s_waitcnt vmcnt(0)
	s_barrier
	s_and_saveexec_b64 s[10:11], s[2:3]
	s_cbranch_execz .LBB0_373
	s_ashr_i32 s9, s8, 31
	s_lshl_b64 s[8:9], s[8:9], 2
	s_add_u32 s8, s13, s8
	s_addc_u32 s9, s14, s9
	global_store_dword v35, v61, s[8:9] sc1
	s_branch .LBB0_373
